# mix_out: idle waves 4-7 also touch the current item's swish-gate block of PM before waves 0-3 need it
# baseline (speedup 1.0000x reference)
.Lspw_0:
	s_lshr_b32 s0, s84, 6
	s_mul_i32 s0, s0, 0x140
	s_cmp_lg_u32 s16, 0
	s_cselect_b32 s1, 0x90, 0
	s_add_i32 s1, s1, 0x60
	s_add_i32 s0, s0, s1
	s_mul_i32 s1, s17, 24
	s_add_i32 s0, s0, s1
	s_lshl_b32 s0, s0, 10
	s_add_u32 s0, s70, s0
	s_addc_u32 s1, s71, 0
	v_subrev_u32_e32 v124, 0x100, v224
	v_lshlrev_b32_e32 v126, 6, v124
	global_load_dword v130, v126, s[0:1]
	v_add_u32_e32 v125, 0x100, v124
	v_min_u32_e32 v125, 0x17f, v125
	v_lshlrev_b32_e32 v126, 6, v125
	global_load_dword v131, v126, s[0:1]
	s_and_b64 vcc, exec, s[62:63]
	s_cbranch_vccnz .Lspw_1
	v_readlane_b32 s0, v253, 40
	v_readlane_b32 s1, v253, 41
	s_lshl_b32 s22, s75, 5
	s_add_i32 s22, s22, s74
	s_mul_i32 s22, s22, 0x120
	s_mul_i32 s60, s77, 0x90
	s_add_i32 s22, s22, s60
	s_add_i32 s22, s22, s76
	s_mul_i32 s22, s22, 0x2400
	s_add_u32 s0, s0, s22
	s_addc_u32 s1, s1, 0
	v_subrev_u32_e32 v124, 0x100, v224
	v_mul_u32_u24_e32 v126, 0x1c72, v124
	v_lshrrev_b32_e32 v126, 20, v126
	v_mul_u32_u24_e32 v126, 0x4ec00, v126
	v_lshl_add_u32 v126, v124, 6, v126
	global_load_dword v127, v126, s[0:1]
	v_add_u32_e32 v125, 0x100, v124
	v_mul_u32_u24_e32 v126, 0x1c72, v125
	v_lshrrev_b32_e32 v126, 20, v126
	v_mul_u32_u24_e32 v126, 0x4ec00, v126
	v_lshl_add_u32 v126, v125, 6, v126
	global_load_dword v128, v126, s[0:1]
	v_add_u32_e32 v125, 0x200, v124
	v_min_u32_e32 v125, 0x23f, v125
	v_mul_u32_u24_e32 v126, 0x1c72, v125
	v_lshrrev_b32_e32 v126, 20, v126
	v_mul_u32_u24_e32 v126, 0x4ec00, v126
	v_lshl_add_u32 v126, v125, 6, v126
	global_load_dword v129, v126, s[0:1]
.Lspw_1:
	s_waitcnt vmcnt(0)
.LBB0_855:
	s_andn2_b64 vcc, exec, s[62:63]
	s_mov_b32 s16, s75
	s_mov_b32 s17, s77
	s_mov_b64 s[84:85], s[82:83]
	s_barrier
	s_cbranch_vccz .LBB0_922
